# baseline with only the per-segment s_setprio flips of the seven GEMM loops deleted (no other change)
# baseline (speedup 1.0000x reference)
;     __device__ __forceinline__ void operator()(f32x4 (&acc)[2][2][4][2], const pg8::Unit& u, int wr, int wc, int fr, int fq) const {
;         const int row0 = u.pm * 256 + wr * 64 + fr, cl0 = wc * 32 + 8 * fq, ch0 = u.pn * 128 + cl0;
;         float sc[2][4];
; #pragma unroll
;         for (int ai = 0; ai < 2; ++ai)
; #pragma unroll
;             for (int m = 0; m < 4; ++m) sc[ai][m] = rf[row0 + ai * 128 + m * 16];
;         {
;             f32x4 sw[2][2];
; #pragma unroll
;             for (int bj = 0; bj < 2; ++bj)
; #pragma unroll
;                 for (int n = 0; n < 2; ++n) { const u32x4 c = *(const u32x4*)(cmax + u.pn * 256 + bj * 128 + cl0 + 4 * n); sw[bj][n] = (f32x4){__uint_as_float(c.x), __uint_as_float(c.y), __uint_as_float(c.z), __uint_as_float(c.w)} * (1.004f / 127.0f); }
; #pragma unroll
;             for (int ai = 0; ai < 2; ++ai)
; #pragma unroll
;                 for (int m = 0; m < 4; ++m)
; #pragma unroll
;                     for (int bj = 0; bj < 2; ++bj)
; #pragma unroll
;                         for (int n = 0; n < 2; ++n) { const i32x4 q = __builtin_bit_cast(i32x4, acc[ai][bj][m][n]); acc[ai][bj][m][n] = (f32x4){(float)q[0], (float)q[1], (float)q[2], (float)q[3]} * sw[bj][n] * sc[ai][m]; }
;         }
;         if ((u.pm & 7) == 7 || u.pm >= MP / 256) {
.LBB0_2523:
	s_lshl_b32 s3, s64, 8
	s_add_i32 s3, s3, s86
	s_lshl_b32 s20, s2, 8
	v_or_b32_e32 v200, s3, v232
	s_ashr_i32 s21, s20, 31
	v_or_b32_e32 v222, 16, v200
	v_lshl_add_u64 v[138:139], s[20:21], 2, v[178:179]
	v_ashrrev_i32_e32 v201, 31, v200
	v_ashrrev_i32_e32 v223, 31, v222
	v_or_b32_e32 v220, 32, v200
	global_load_dwordx4 v[130:133], v[138:139], off
	global_load_dwordx4 v[134:137], v[138:139], off offset:16
	v_lshl_add_u64 v[142:143], v[200:201], 2, s[26:27]
	v_lshl_add_u64 v[140:141], v[222:223], 2, s[26:27]
	v_ashrrev_i32_e32 v221, 31, v220
	v_or_b32_e32 v218, 48, v200
	global_load_dword v212, v[142:143], off
	global_load_dword v210, v[140:141], off
	v_lshl_add_u64 v[140:141], v[220:221], 2, s[26:27]
	v_ashrrev_i32_e32 v219, 31, v218
	global_load_dword v208, v[140:141], off
	global_load_dword v198, v[142:143], off offset:512
	v_lshl_add_u64 v[140:141], v[218:219], 2, s[26:27]
	global_load_dword v206, v[140:141], off
	global_load_dword v196, v[142:143], off offset:576
	v_cvt_f32_i32_e32 v145, v107
	v_cvt_f32_i32_e32 v144, v106
	v_cvt_f32_i32_e32 v147, v109
	v_cvt_f32_i32_e32 v146, v108
	global_load_dwordx4 v[106:109], v[138:139], off offset:528
	s_nop 0
	global_load_dwordx4 v[138:141], v[138:139], off offset:512
	s_nop 0
	global_load_dword v192, v[142:143], off offset:640
	global_load_dword v190, v[142:143], off offset:704
	v_cvt_f32_i32_e32 v115, v115
	v_cvt_f32_i32_e32 v114, v114
	v_cvt_f32_i32_e32 v127, v127
	v_cvt_f32_i32_e32 v126, v126
	v_cvt_f32_i32_e32 v117, v117
	v_cvt_f32_i32_e32 v116, v116
	v_cvt_f32_i32_e32 v95, v95
	v_cvt_f32_i32_e32 v94, v94
	v_cvt_f32_i32_e32 v149, v87
	v_cvt_f32_i32_e32 v148, v86
	v_cvt_f32_i32_e32 v151, v89
	v_cvt_f32_i32_e32 v150, v88
	v_cvt_f32_i32_e32 v129, v129
	v_cvt_f32_i32_e32 v128, v128
	v_cvt_f32_i32_e32 v97, v97
	v_cvt_f32_i32_e32 v96, v96
	v_cvt_f32_i32_e32 v63, v63
	v_cvt_f32_i32_e32 v65, v65
	v_cvt_f32_i32_e32 v64, v64
	v_cvt_f32_i32_e32 v62, v62
	v_cvt_f32_i32_e32 v55, v55
	v_cvt_f32_i32_e32 v57, v57
	v_cvt_f32_i32_e32 v56, v56
	v_cvt_f32_i32_e32 v54, v54
	s_and_b32 s33, s64, 7
	v_cvt_f32_i32_e32 v51, v51
	v_cvt_f32_i32_e32 v53, v53
	v_cvt_f32_i32_e32 v52, v52
	v_cvt_f32_i32_e32 v50, v50
	s_cmp_eq_u32 s33, 7
	v_cvt_f32_i32_e32 v123, v123
	v_cvt_f32_i32_e32 v122, v122
	v_cvt_f32_i32_e32 v125, v125
	v_cvt_f32_i32_e32 v124, v124
	v_cvt_f32_i32_e32 v103, v103
	v_cvt_f32_i32_e32 v102, v102
	v_cvt_f32_i32_e32 v105, v105
	v_cvt_f32_i32_e32 v104, v104
	v_cvt_f32_i32_e32 v79, v79
	v_cvt_f32_i32_e32 v81, v81
	v_cvt_f32_i32_e32 v80, v80
	v_cvt_f32_i32_e32 v78, v78
	v_cvt_f32_i32_e32 v71, v71
	v_cvt_f32_i32_e32 v73, v73
	v_cvt_f32_i32_e32 v72, v72
	v_cvt_f32_i32_e32 v70, v70
	v_cvt_f32_i32_e32 v19, v19
	v_cvt_f32_i32_e32 v21, v21
	v_cvt_f32_i32_e32 v20, v20
	v_cvt_f32_i32_e32 v18, v18
	s_cselect_b64 s[66:67], -1, 0
	s_cmp_lg_u32 s33, 7
	s_cselect_b64 s[68:69], -1, 0
	s_cmp_lt_i32 s64, 32
	s_cselect_b64 s[62:63], -1, 0
	s_cmp_gt_i32 s64, 31
	s_cselect_b64 s[20:21], -1, 0
	v_lshl_or_b32 v194, s2, 7, v242
	s_or_b64 s[20:21], s[20:21], s[66:67]
	v_add_u32_e32 v219, 0x80, v200
	s_waitcnt vmcnt(0)
;     __device__ __forceinline__ void operator()(f32x4 (&acc)[2][2][4][2], const pg8::Unit& u, int wr, int wc, int fr, int fq) const {
;     ...
;                 for (int n = 0; n < 2; ++n) { const u32x4 c = *(const u32x4*)(cmax + u.pn * 256 + bj * 128 + cl0 + 4 * n); sw[bj][n] = (f32x4){__uint_as_float(c.x), __uint_as_float(c.y), __uint_as_float(c.z), __uint_as_float(c.w)} * (1.004f / 127.0f); }
; #pragma unroll
;             for (int ai = 0; ai < 2; ++ai)
; #pragma unroll
;                 for (int m = 0; m < 4; ++m)
; #pragma unroll
;                     for (int bj = 0; bj < 2; ++bj)
; #pragma unroll
;                         for (int n = 0; n < 2; ++n) { const i32x4 q = __builtin_bit_cast(i32x4, acc[ai][bj][m][n]); acc[ai][bj][m][n] = (f32x4){(float)q[0], (float)q[1], (float)q[2], (float)q[3]} * sw[bj][n] * sc[ai][m]; }
;         }
;         if ((u.pm & 7) == 7 || u.pm >= MP / 256) {
; #pragma unroll
;             for (int ai = 0; ai < 2; ++ai)
; #pragma unroll
;                 for (int m = 0; m < 4; ++m) { const int row = row0 + ai * 128 + m * 16; float* so = nullptr;
;                     if (row < MP) { const int t = row & (SEQ - 1); if (t >= SEQ - 2) so = out + O_PFC + ((size_t)(row >> 11) * 2 + (t - (SEQ - 2))) * DFF + ch0; }
;                     else { const int r = row - MP, t = r & 3; if (t >= 2) so = out + O_SFC + ((size_t)(r >> 2) * 2 + (t - 2)) * DFF + ch0; }
;                     if (so) { *(f32x4*)so = acc[ai][0][m][0]; *(f32x4*)(so + 4) = acc[ai][0][m][1]; } } }
	v_pk_mul_f32 v[130:131], v[130:131], s[0:1] op_sel_hi:[1,0]
	v_pk_mul_f32 v[152:153], v[134:135], s[0:1] op_sel_hi:[1,0]
	v_pk_mul_f32 v[132:133], v[132:133], s[0:1] op_sel_hi:[1,0]
	v_pk_mul_f32 v[142:143], v[136:137], s[0:1] op_sel_hi:[1,0]
	v_pk_mul_f32 v[114:115], v[130:131], v[114:115]
	v_pk_mul_f32 v[144:145], v[152:153], v[144:145]
	v_pk_mul_f32 v[88:89], v[130:131], v[126:127]
	v_pk_mul_f32 v[116:117], v[132:133], v[116:117]
	v_pk_mul_f32 v[146:147], v[142:143], v[146:147]
	v_pk_mul_f32 v[160:161], v[152:153], v[94:95]
	v_pk_mul_f32 v[126:127], v[210:211], v[114:115] op_sel_hi:[0,1]
	v_pk_mul_f32 v[94:95], v[210:211], v[144:145] op_sel_hi:[0,1]
	v_pk_mul_f32 v[114:115], v[132:133], v[150:151]
	v_pk_mul_f32 v[144:145], v[130:131], v[148:149]
	v_pk_mul_f32 v[86:87], v[132:133], v[128:129]
	v_pk_mul_f32 v[158:159], v[142:143], v[96:97]
	v_pk_mul_f32 v[128:129], v[210:211], v[116:117] op_sel_hi:[0,1]
	v_pk_mul_f32 v[96:97], v[210:211], v[146:147] op_sel_hi:[0,1]
	v_pk_mul_f32 v[116:117], v[206:207], v[114:115] op_sel_hi:[0,1]
	v_pk_mul_f32 v[114:115], v[206:207], v[144:145] op_sel_hi:[0,1]
	v_cvt_f32_i32_e32 v145, v39
	v_cvt_f32_i32_e32 v147, v41
	v_cvt_f32_i32_e32 v146, v40
	v_cvt_f32_i32_e32 v144, v38
	v_pk_mul_f32 v[64:65], v[142:143], v[64:65]
	v_pk_mul_f32 v[62:63], v[152:153], v[62:63]
	v_pk_mul_f32 v[40:41], v[198:199], v[64:65] op_sel_hi:[0,1]
	v_pk_mul_f32 v[38:39], v[198:199], v[62:63] op_sel_hi:[0,1]
	v_pk_mul_f32 v[64:65], v[132:133], v[146:147]
	v_pk_mul_f32 v[62:63], v[130:131], v[144:145]
	v_cvt_f32_i32_e32 v145, v31
	v_cvt_f32_i32_e32 v147, v33
	v_cvt_f32_i32_e32 v146, v32
	v_cvt_f32_i32_e32 v144, v30
	v_pk_mul_f32 v[56:57], v[142:143], v[56:57]
	v_pk_mul_f32 v[54:55], v[152:153], v[54:55]
	v_pk_mul_f32 v[32:33], v[196:197], v[56:57] op_sel_hi:[0,1]
	v_pk_mul_f32 v[30:31], v[196:197], v[54:55] op_sel_hi:[0,1]
	v_pk_mul_f32 v[56:57], v[132:133], v[146:147]
	v_pk_mul_f32 v[54:55], v[130:131], v[144:145]
	v_cvt_f32_i32_e32 v145, v27
	v_cvt_f32_i32_e32 v147, v29
	v_cvt_f32_i32_e32 v146, v28
	v_cvt_f32_i32_e32 v144, v26
	v_pk_mul_f32 v[52:53], v[142:143], v[52:53]
	v_pk_mul_f32 v[50:51], v[152:153], v[50:51]
	v_pk_mul_f32 v[124:125], v[142:143], v[124:125]
	v_pk_mul_f32 v[122:123], v[152:153], v[122:123]
	v_pk_mul_f32 v[154:155], v[132:133], v[104:105]
	v_pk_mul_f32 v[156:157], v[130:131], v[102:103]
	v_pk_mul_f32 v[80:81], v[142:143], v[80:81]
	v_pk_mul_f32 v[78:79], v[152:153], v[78:79]
	v_pk_mul_f32 v[72:73], v[132:133], v[72:73]
	v_pk_mul_f32 v[70:71], v[130:131], v[70:71]
	v_pk_mul_f32 v[26:27], v[192:193], v[50:51] op_sel_hi:[0,1]
	v_pk_mul_f32 v[28:29], v[192:193], v[52:53] op_sel_hi:[0,1]
	v_pk_mul_f32 v[52:53], v[132:133], v[146:147]
	v_pk_mul_f32 v[50:51], v[130:131], v[144:145]
	v_pk_mul_f32 v[20:21], v[142:143], v[20:21]
	v_pk_mul_f32 v[18:19], v[152:153], v[18:19]
	v_add_u32_e32 v201, 0xb0, v200
	v_pk_mul_f32 v[134:135], v[212:213], v[88:89] op_sel_hi:[0,1]
	v_pk_mul_f32 v[136:137], v[212:213], v[86:87] op_sel_hi:[0,1]
	v_pk_mul_f32 v[102:103], v[212:213], v[122:123] op_sel_hi:[0,1]
	v_pk_mul_f32 v[104:105], v[212:213], v[124:125] op_sel_hi:[0,1]
	v_pk_mul_f32 v[124:125], v[208:209], v[154:155] op_sel_hi:[0,1]
	v_pk_mul_f32 v[122:123], v[208:209], v[156:157] op_sel_hi:[0,1]
	v_pk_mul_f32 v[88:89], v[208:209], v[158:159] op_sel_hi:[0,1]
	v_pk_mul_f32 v[86:87], v[208:209], v[160:161] op_sel_hi:[0,1]
	v_pk_mul_f32 v[80:81], v[206:207], v[80:81] op_sel_hi:[0,1]
	v_pk_mul_f32 v[78:79], v[206:207], v[78:79] op_sel_hi:[0,1]
	v_pk_mul_f32 v[70:71], v[198:199], v[70:71] op_sel_hi:[0,1]
	v_pk_mul_f32 v[72:73], v[198:199], v[72:73] op_sel_hi:[0,1]
	v_pk_mul_f32 v[62:63], v[196:197], v[62:63] op_sel_hi:[0,1]
	v_pk_mul_f32 v[64:65], v[196:197], v[64:65] op_sel_hi:[0,1]
	v_pk_mul_f32 v[54:55], v[192:193], v[54:55] op_sel_hi:[0,1]
	v_pk_mul_f32 v[56:57], v[192:193], v[56:57] op_sel_hi:[0,1]
	v_pk_mul_f32 v[50:51], v[190:191], v[50:51] op_sel_hi:[0,1]
	v_pk_mul_f32 v[52:53], v[190:191], v[52:53] op_sel_hi:[0,1]
	v_pk_mul_f32 v[18:19], v[190:191], v[18:19] op_sel_hi:[0,1]
	v_pk_mul_f32 v[20:21], v[190:191], v[20:21] op_sel_hi:[0,1]
	s_andn2_b64 vcc, exec, s[20:21]
	v_ashrrev_i32_e32 v195, 31, v194
	s_cbranch_vccnz .LBB0_2557
	v_cmp_lt_i32_e32 vcc, s95, v200
	s_and_b64 s[70:71], vcc, s[36:37]
	v_mov_b64_e32 v[130:131], 0
	s_and_saveexec_b64 s[20:21], s[70:71]
	v_add_u32_e32 v130, 0xffffe000, v200
	v_lshrrev_b32_e32 v130, 1, v130
	v_and_b32_e32 v130, 0x7fffffe6, v130
	v_add_u32_e32 v132, v130, v243
	v_mov_b64_e32 v[130:131], s[34:35]
	v_mad_u64_u32 v[130:131], s[70:71], v132, s94, v[130:131]
	v_lshl_add_u64 v[130:131], v[194:195], 2, v[130:131]
	s_or_b64 exec, exec, s[20:21]
	v_cmp_ne_u64_e32 vcc, 0, v[130:131]
	s_and_saveexec_b64 s[20:21], vcc
	s_cbranch_execz .LBB0_2528
	global_store_dwordx4 v[130:131], v[134:137], off
	global_store_dwordx4 v[130:131], v[102:105], off offset:16

; __device__ __forceinline__ unsigned cvt_pk_bf16(float lo, float hi) { unsigned r; asm("v_cvt_pk_bf16_f32 %0, %1, %2" : "=v"(r) : "v"(lo), "v"(hi)); return r; }
; __device__ __forceinline__ float gelu_tanh(float x) { const float u = 0.7978845608028654f * (x + 0.044715f * x * x * x); return x * sigmoidf_(2.0f * u); }
; #define PG8_WAIT_V(n) asm volatile("s_waitcnt vmcnt(" #n ")" ::: "memory")
; #define PG8_BAR __builtin_amdgcn_s_barrier()
; template <class Epi, class Geom, class Sched, bool ALIGN_EPI, bool I8 = false>
; __device__ __forceinline__ void gemm_phase(LAS unsigned char* lds, const Gemm g, const Sched& S, const Epi& E) {
;     ...
;         cur = nxt; cA = nA; cB = nB; ++ui;
;         if constexpr (ALIGN_EPI) { if (wr == 1) PG8_BAR; }
;     }
;     PG8_WAIT_V(0);
;     if constexpr (!ALIGN_EPI) { if (wr == 0) PG8_BAR; }
;     PG8_BAR;
;     __device__ __forceinline__ void operator()(f32x4 (&acc)[2][2][4][2], const pg8::Unit& u, int wr, int wc, int fr, int fq) const {
;     ...
;                 for (int m = 0; m < 4; ++m) { const int row = row0 + ai * 128 + m * 16; const f32x4 g = acc[ai][0][m][n], vv = acc[ai][1][m][n]; f32x4 p1, p2;
;                     if (prompt) { const f32x4 gp = (m == 0) ? hal[n] : acc[ai][0][m > 0 ? m - 1 : 0][n];
; #pragma unroll
;                         for (int j = 0; j < 4; ++j) { p1[j] = dpp_ror1(fr == 15 ? gp[j] : g[j]); p2[j] = dpp_ror2(fr >= 14 ? gp[j] : g[j]); } }
;                     else { const int t = fr & 3; const float* sp = stf + (size_t)((row - MP) >> 2) * 2 * DFF + ch0 + 4 * n;
;                         f32x4 b0 = (f32x4){0.f, 0.f, 0.f, 0.f}, b1 = b0; if (t == 0) b0 = *(const f32x4*)sp; if (t <= 1) b1 = *(const f32x4*)(sp + DFF);
; #pragma unroll
;                         for (int j = 0; j < 4; ++j) { const float r1 = dpp_ror1(g[j]), r2 = dpp_ror2(g[j]); p1[j] = t >= 1 ? r1 : b1[j]; p2[j] = t >= 2 ? r2 : (t == 1 ? b1[j] : b0[j]); } }
;                     float o[4];
; #pragma unroll
;                     for (int j = 0; j < 4; ++j) { const float y = bb[j] + w0[j] * p2[j] + w1[j] * p1[j] + w2[j] * g[j]; o[j] = gelu_tanh(y) * vv[j]; }
;                     u32x2 w; w.x = cvt_pk_bf16(o[0], o[1]); w.y = cvt_pk_bf16(o[2], o[3]);
;                     *(u32x2*)(ACT + (size_t)row * DFF + ch0 + 4 * n) = w; } } }
.LBB0_2734:
	v_mov_b32_e32 v19, v6
	v_fma_f32 v15, v42, v16, v34
	v_pk_mul_f32 v[16:17], v[54:55], v[18:19]
	v_cvt_f32_i32_e32 v5, v5
	v_add_f32_e32 v6, v17, v15
	v_add_f32_e32 v15, v16, v6
	v_mul_f32_e32 v6, 0x3d372713, v15
	v_mul_f32_e32 v6, v15, v6
	v_fma_f32 v6, v15, v6, v15
	v_mul_f32_e32 v6, 0x3f4c422a, v6
	v_add_f32_e32 v6, v6, v6
	v_cvt_f32_i32_e32 v4, v4
	v_mul_f32_e32 v6, 0xbfb8aa3b, v6
	v_exp_f32_e32 v6, v6
	v_mov_b32_e32 v16, v190
	v_pk_mul_f32 v[4:5], v[124:125], v[4:5]
	v_mov_b32_e32 v17, v190
	v_pk_mul_f32 v[4:5], v[16:17], v[4:5]
	v_add_f32_e32 v6, 1.0, v6
	v_fma_f32 v17, v43, v13, v35
	v_mov_b32_e32 v13, v7
	v_rcp_f32_e32 v16, v6
	v_pk_mul_f32 v[6:7], v[22:23], v[12:13]
	v_cvt_f32_i32_e32 v3, v3
	v_add_f32_e32 v7, v7, v17
	v_add_f32_e32 v12, v6, v7
	v_mul_f32_e32 v6, 0x3d372713, v12
	v_mul_f32_e32 v6, v12, v6
	v_fma_f32 v6, v12, v6, v12
	v_mul_f32_e32 v6, 0x3f4c422a, v6
	v_add_f32_e32 v6, v6, v6
	v_cvt_f32_i32_e32 v2, v2
	v_mul_f32_e32 v6, 0xbfb8aa3b, v6
	v_exp_f32_e32 v6, v6
	v_mul_f32_e32 v7, v15, v16
	v_pk_mul_f32 v[2:3], v[122:123], v[2:3]
	v_mov_b32_e32 v21, v8
	v_pk_mul_f32 v[2:3], v[190:191], v[2:3]
	v_add_f32_e32 v6, 1.0, v6
	v_mul_f32_e32 v2, v2, v7
	v_rcp_f32_e32 v13, v6
	v_fma_f32 v14, v44, v14, v36
	v_pk_mul_f32 v[6:7], v[50:51], v[20:21]
	v_fmac_f32_e32 v37, v45, v11
	v_add_f32_e32 v7, v7, v14
	v_add_f32_e32 v8, v6, v7
	v_mul_f32_e32 v6, 0x3d372713, v8
	v_mul_f32_e32 v6, v8, v6
	v_fma_f32 v6, v8, v6, v8
	v_mul_f32_e32 v6, 0x3f4c422a, v6
	v_add_f32_e32 v6, v6, v6
	v_mul_f32_e32 v6, 0xbfb8aa3b, v6
	v_mov_b32_e32 v11, v9
	v_exp_f32_e32 v14, v6
	v_pk_mul_f32 v[6:7], v[24:25], v[10:11]
	v_mul_f32_e32 v9, v12, v13
	v_add_f32_e32 v7, v7, v37
	v_add_f32_e32 v6, v6, v7
	v_mul_f32_e32 v7, 0x3d372713, v6
	v_mul_f32_e32 v7, v6, v7
	v_fma_f32 v7, v6, v7, v6
	v_mul_f32_e32 v7, 0x3f4c422a, v7
	v_add_f32_e32 v7, v7, v7
	v_mul_f32_e32 v7, 0xbfb8aa3b, v7
	v_exp_f32_e32 v7, v7
	v_add_f32_e32 v10, 1.0, v14
	v_rcp_f32_e32 v10, v10
	v_mul_f32_e32 v3, v3, v9
	v_add_f32_e32 v7, 1.0, v7
	v_rcp_f32_e32 v7, v7
	v_mul_f32_e32 v8, v8, v10
	s_andn2_b64 vcc, exec, s[18:19]
	s_mov_b64 s[2:3], -1
	v_mul_f32_e32 v6, v6, v7
	v_mul_f32_e32 v4, v4, v8
	v_mul_f32_e32 v5, v5, v6
	v_cvt_pk_bf16_f32 v2, v2, v3
	v_cvt_pk_bf16_f32 v3, v4, v5
	global_store_dwordx2 v[64:65], v[2:3], off offset:8
	s_cbranch_vccnz .LBB0_2516
	v_readlane_b32 s2, v255, 19
	v_readlane_b32 s3, v255, 20
	s_andn2_b64 vcc, exec, s[2:3]
	s_cbranch_vccnz .LBB0_2515
	s_barrier
	s_branch .LBB0_2515
.LBB0_2737:
	s_waitcnt vmcnt(0)
	v_readlane_b32 s72, v254, 41
	v_readlane_b32 s90, v254, 63
	v_readlane_b32 s20, v255, 3
	s_mov_b32 s92, s8
	v_readlane_b32 s82, v254, 51
	v_readlane_b32 s83, v254, 52
	v_readlane_b32 s84, v254, 53
	v_readlane_b32 s85, v254, 54
	v_readlane_b32 s86, v254, 55
	v_readlane_b32 s87, v254, 56
	v_readlane_b32 s91, v255, 0
	v_readlane_b32 s21, v255, 4
	s_barrier
	v_readlane_b32 s73, v254, 42
	v_readlane_b32 s74, v254, 43
	v_readlane_b32 s75, v254, 44
	v_readlane_b32 s76, v254, 45
	v_readlane_b32 s77, v254, 46
	v_readlane_b32 s78, v254, 47
	v_readlane_b32 s79, v254, 48
	v_readlane_b32 s80, v254, 49
	v_readlane_b32 s81, v254, 50
